# v93 + P6 up-GEMM unit order with 4 row panels x 8 column tiles per XCD round (group size 4): less operand traffic from beyond L2
# speedup vs baseline: 1.0190x; 1.0018x over previous
; #define PG8_STAGE(bufoff, gbase, voff) do { _Pragma("unroll") for (int _i = 0; _i < 2; ++_i) \
;         __builtin_amdgcn_global_load_lds((const unsigned*)((const char*)(gbase) + (voff)[_i]), (LAS unsigned*)(lds + (bufoff) + ldsw + _i * 8192), 16, 0, 0); } while (0)
; #define PG8_WAIT_V(n) asm volatile("s_waitcnt vmcnt(" #n ")" ::: "memory")
; #define PG8_BAR __builtin_amdgcn_s_barrier()
;     __host__ __device__ bool next(int i, Unit& u) const {
;     ...
;         int wgid = (int)L; { const int q = nwg / NXCD, r = nwg % NXCD, xcd = wgid % NXCD, off = wgid / NXCD; wgid = (xcd < r ? xcd * (q + 1) : r * (q + 1) + (xcd - r) * q) + off; }
;         const int nig = WGM * nN, gid = wgid / nig, fm = gid * WGM, gsz = (nM - fm) < WGM ? (nM - fm) : WGM;
;         u.pm = fm + ((wgid % nig) % gsz); u.pn = (wgid % nig) / gsz; return true;
; template <class Epi, class Sched>
; __device__ __forceinline__ void gemm_phase(LAS unsigned char* lds, const Gemm g, const Sched& S, const Epi& E) {
;     ...
;     const char* cA = (const char*)g.A + (size_t)cur.pm * tstepA; const char* cB = (const char*)g.Bt + (size_t)cur.pn * tstepB;
;     PG8_STAGE(PG8_SB(0, 0), cB, voffB); PG8_STAGE(PG8_SB(0, 1), cB + hstepB, voffB); PG8_STAGE(PG8_SA(0, 0), cA, voffA); PG8_STAGE(PG8_SA(0, 1), cA + hstepA, voffA);
;     if (wr == 1) PG8_BAR;
;     PG8_WAIT_V(2); PG8_BAR;
;     PG8_STAGE(PG8_SB(1, 0), cB + kstep, voffB); PG8_STAGE(PG8_SA(1, 0), cA + kstep, voffA); PG8_STAGE(PG8_SB(1, 1), cB + hstepB + kstep, voffB);
;     PG8_WAIT_V(6); PG8_BAR;
.LBB0_924:
	s_or_b64 exec, exec, s[0:1]
	s_cmpk_gt_i32 s2, 0x83f
	v_readfirstlane_b32 s5, v188
	s_waitcnt lgkmcnt(0)
	s_barrier
	s_cbranch_scc1 .LBB0_940
	v_lshrrev_b32_e32 v0, 5, v188
	v_lshrrev_b32_e32 v2, 1, v188
	v_and_b32_e32 v0, 4, v0
	v_bfe_u32 v1, v188, 2, 2
	v_and_b32_e32 v11, 24, v2
	v_or3_b32 v0, v0, v1, v11
	v_lshlrev_b32_e32 v1, 4, v188
	v_add_u32_e32 v8, 0x2000, v1
	v_lshrrev_b32_e32 v2, 7, v8
	s_movk_i32 s0, 0xe0
	v_and_b32_e32 v4, 32, v188
	v_and_or_b32 v3, v2, s0, v0
	v_bitop3_b32 v9, v1, v4, 48 bitop3:0x6c
	v_and_b32_e32 v10, 64, v188
	v_bfe_u32 v12, v188, 2, 4
	s_movk_i32 s0, 0xf0
	v_or_b32_e32 v1, v9, v10
	v_and_or_b32 v2, v2, s0, v12
	v_lshl_or_b32 v130, v2, 12, v1
	v_lshrrev_b32_e32 v2, 3, v188
	s_movk_i32 s0, 0x60
	v_and_or_b32 v0, v2, s0, v0
	s_movk_i32 s0, 0x70
	s_ashr_i32 s33, s2, 31
	v_lshl_or_b32 v132, v0, 12, v1
	v_and_or_b32 v0, v2, s0, v12
	s_lshr_b32 s0, s33, 29
	s_add_i32 s0, s2, s0
	s_lshr_b32 s10, s5, 6
	s_ashr_i32 s1, s0, 3
	s_and_b32 s0, s0, -8
	s_lshr_b32 s14, s5, 8
	s_lshl_b32 s3, s10, 10
	s_sub_i32 s0, s2, s0
	s_cmp_lt_i32 s0, 0
	s_movk_i32 s40, 0x109
	s_cselect_b32 s4, s40, 0x108
	s_mul_i32 s0, s0, s4
	s_add_i32 s0, s0, s1
	s_lshr_b32 s4, s0, 7
	s_and_b32 s1, s0, 127
	s_lshl_b32 s8, s4, 2
	s_lshr_b32 s4, s1, 2
	s_and_b32 s0, s1, 3
	s_add_i32 s0, s8, s0
	s_ashr_i32 s1, s0, 31
	s_bfe_i64 s[16:17], s[4:5], 0x100000
	s_lshl_b64 s[8:9], s[0:1], 20
	s_lshl_b64 s[16:17], s[16:17], 20
	s_add_u32 s36, s66, s16
	s_addc_u32 s37, s67, s17
	s_add_i32 s41, s3, 0
	s_add_i32 m0, s41, 0x10000
	v_lshl_or_b32 v128, v3, 12, v1
	global_load_lds_dwordx4 v132, s[36:37]
	s_add_i32 m0, s41, 0x12000
	s_add_u32 s16, s36, 0x80000
	global_load_lds_dwordx4 v128, s[36:37]
	s_addc_u32 s17, s37, 0
	s_add_i32 m0, s41, 0x14000
	v_lshl_or_b32 v134, v0, 12, v1
	global_load_lds_dwordx4 v132, s[16:17]
	s_add_i32 m0, s41, 0x16000
	s_add_u32 s34, s12, s8
	s_addc_u32 s35, s13, s9
	s_add_i32 s42, s41, 0x2000
	global_load_lds_dwordx4 v128, s[16:17]
	s_mov_b32 m0, s41
	s_add_u32 s8, s34, 0x80000
	global_load_lds_dwordx4 v134, s[34:35]
	s_mov_b32 m0, s42
	s_addc_u32 s9, s35, 0
	s_add_i32 s43, s41, 0x4000
	global_load_lds_dwordx4 v130, s[34:35]
	s_mov_b32 m0, s43
	s_add_i32 s44, s41, 0x6000
	global_load_lds_dwordx4 v134, s[8:9]
	s_mov_b32 m0, s44
	v_mov_b32_e32 v133, 0
	global_load_lds_dwordx4 v130, s[8:9]
	v_mov_b32_e32 v129, v133
	v_mov_b32_e32 v135, v133
	v_mov_b32_e32 v131, v133
	s_cmp_eq_u32 s14, 1
	s_mov_b32 s45, 0
	v_lshl_add_u64 v[6:7], s[36:37], 0, v[132:133]
	v_lshl_add_u64 v[4:5], s[36:37], 0, v[128:129]
	v_lshl_add_u64 v[0:1], s[34:35], 0, v[134:135]
	s_cselect_b64 s[8:9], -1, 0
	s_cmp_lg_u32 s14, 1
	v_lshl_add_u64 v[2:3], s[34:35], 0, v[130:131]
	s_cbranch_scc1 .LBB0_927
	s_barrier

;     __host__ __device__ bool next(int i, Unit& u) const {
;         const long L = (long)i * G + c; if (L >= nwg) return false;
;         int wgid = (int)L; { const int q = nwg / NXCD, r = nwg % NXCD, xcd = wgid % NXCD, off = wgid / NXCD; wgid = (xcd < r ? xcd * (q + 1) : r * (q + 1) + (xcd - r) * q) + off; }
;         const int nig = WGM * nN, gid = wgid / nig, fm = gid * WGM, gsz = (nM - fm) < WGM ? (nM - fm) : WGM;
;         u.pm = fm + ((wgid % nig) % gsz); u.pn = (wgid % nig) / gsz; return true;
.LBB0_930:
	s_add_i32 s45, s45, 1
	s_mul_i32 s4, s45, s48
	s_mul_hi_u32 s5, s45, s49
	s_add_i32 s5, s5, s4
	s_mul_i32 s4, s45, s49
	s_add_u32 s28, s4, s2
	s_addc_u32 s29, s5, s33
	v_cmp_gt_i64_e32 vcc, s[28:29], v[142:143]
	v_cmp_lt_i64_e64 s[4:5], s[28:29], v[140:141]
	s_cbranch_vccnz .LBB0_932
	s_ashr_i32 s24, s28, 31
	s_lshr_b32 s24, s24, 29
	s_add_i32 s24, s28, s24
	s_ashr_i32 s25, s24, 3
	s_and_b32 s24, s24, -8
	s_sub_i32 s24, s28, s24
	s_cmp_lt_i32 s24, 0
	s_cselect_b32 s26, s40, 0x108
	s_mul_i32 s24, s24, s26
	s_add_i32 s24, s24, s25
	s_ashr_i32 s25, s24, 31
	s_lshr_b32 s25, s25, 25
	s_add_i32 s25, s24, s25
	s_ashr_i32 s26, s25, 7
	s_lshl_b32 s26, s26, 2
	s_sub_i32 s27, 0x42, s26
	s_min_i32 s27, s27, 4
	s_abs_i32 s28, s27
	v_cvt_f32_u32_e32 v0, s28
	s_sub_i32 s30, 0, s28
	s_andn2_b32 s25, s25, 127
	s_sub_i32 s25, s24, s25
	v_rcp_iflag_f32_e32 v0, v0
	s_abs_i32 s24, s25
	s_xor_b32 s29, s25, s27
	s_ashr_i32 s29, s29, 31
	v_mul_f32_e32 v0, 0x4f7ffffe, v0
	v_cvt_u32_f32_e32 v0, v0
	s_nop 0
	v_readfirstlane_b32 s31, v0
	s_mul_i32 s30, s30, s31
	s_mul_hi_u32 s30, s31, s30
	s_add_i32 s31, s31, s30
	s_mul_hi_u32 s30, s24, s31
	s_mul_i32 s31, s30, s28
	s_sub_i32 s24, s24, s31
	s_add_i32 s38, s30, 1
	s_sub_i32 s31, s24, s28
	s_cmp_ge_u32 s24, s28
	s_cselect_b32 s30, s38, s30
	s_cselect_b32 s24, s31, s24
	s_add_i32 s31, s30, 1
	s_cmp_ge_u32 s24, s28
	s_cselect_b32 s24, s31, s30
	s_xor_b32 s24, s24, s29
	s_sub_i32 s24, s24, s29
	s_mul_i32 s27, s24, s27
	s_sub_i32 s25, s25, s27
	s_add_i32 s26, s26, s25
